# v9 + removed the back-to-back s_setprio 0 / s_setprio 1 pair in the middle of every GEMM MFMA segment (16 sites)
# baseline (speedup 1.0000x reference)
.LBB0_41:
	s_add_u32 s20, s8, s18
	s_addc_u32 s21, s9, s19
	s_add_i32 s56, 0, 0x10000
	s_cmpk_eq_i32 s55, 0x7c
	s_cselect_b32 s23, s37, s21
	s_cselect_b32 s22, s51, s20
	s_cselect_b32 s21, s11, s54
	s_cselect_b32 s20, s52, s53
	s_add_i32 s58, 0, 0x14000
	v_add_u32_e32 v160, s56, v146
	v_add_u32_e32 v176, s58, v146
	ds_read_b128 v[148:151], v160
	ds_read_b128 v[152:155], v160 offset:1024
	ds_read_b128 v[156:159], v160 offset:2048
	ds_read_b128 v[160:163], v160 offset:3072
	ds_read_b128 v[164:167], v176
	ds_read_b128 v[168:171], v176 offset:1024
	ds_read_b128 v[172:175], v176 offset:2048
	ds_read_b128 v[176:179], v176 offset:3072
	v_lshl_add_u64 v[212:213], s[8:9], 0, v[140:141]
	s_add_i32 m0, s42, 0xc000
	ds_read_b128 v[180:183], v147
	ds_read_b128 v[184:187], v147 offset:1024
	ds_read_b128 v[188:191], v147 offset:2048
	ds_read_b128 v[192:195], v147 offset:3072
	ds_read_b128 v[196:199], v147 offset:4096
	ds_read_b128 v[200:203], v147 offset:5120
	ds_read_b128 v[204:207], v147 offset:6144
	ds_read_b128 v[208:211], v147 offset:7168
	global_load_lds_dwordx4 v[212:213], off
	v_lshl_add_u64 v[212:213], s[8:9], 0, v[142:143]
	s_add_i32 m0, s42, 0xe000
	s_nop 0
	global_load_lds_dwordx4 v[212:213], off
	s_waitcnt vmcnt(8)
	s_waitcnt lgkmcnt(0)
	s_barrier
	s_setprio 1
	s_waitcnt lgkmcnt(0)
	v_mfma_f32_16x16x32_bf16 v[92:95], v[148:151], v[180:183], v[92:95]
	v_mfma_f32_16x16x32_bf16 v[60:63], v[156:159], v[180:183], v[60:63]
	v_mfma_f32_16x16x32_bf16 v[88:91], v[148:151], v[188:191], v[88:91]
	v_mfma_f32_16x16x32_bf16 v[56:59], v[156:159], v[188:191], v[56:59]
	v_mfma_f32_16x16x32_bf16 v[84:87], v[148:151], v[196:199], v[84:87]
	v_mfma_f32_16x16x32_bf16 v[52:55], v[156:159], v[196:199], v[52:55]
	v_mfma_f32_16x16x32_bf16 v[80:83], v[148:151], v[204:207], v[80:83]
	v_mfma_f32_16x16x32_bf16 v[48:51], v[156:159], v[204:207], v[48:51]
	v_mfma_f32_16x16x32_bf16 v[92:95], v[152:155], v[184:187], v[92:95]
	v_mfma_f32_16x16x32_bf16 v[60:63], v[160:163], v[184:187], v[60:63]
	v_mfma_f32_16x16x32_bf16 v[88:91], v[152:155], v[192:195], v[88:91]
	v_mfma_f32_16x16x32_bf16 v[56:59], v[160:163], v[192:195], v[56:59]
	v_mfma_f32_16x16x32_bf16 v[84:87], v[152:155], v[200:203], v[84:87]
	v_mfma_f32_16x16x32_bf16 v[52:55], v[160:163], v[200:203], v[52:55]
	v_mfma_f32_16x16x32_bf16 v[80:83], v[152:155], v[208:211], v[80:83]
	v_mfma_f32_16x16x32_bf16 v[48:51], v[160:163], v[208:211], v[48:51]
	v_mfma_f32_16x16x32_bf16 v[28:31], v[164:167], v[180:183], v[28:31]
	v_mfma_f32_16x16x32_bf16 v[12:15], v[172:175], v[180:183], v[12:15]
	v_mfma_f32_16x16x32_bf16 v[24:27], v[164:167], v[188:191], v[24:27]
	v_mfma_f32_16x16x32_bf16 v[8:11], v[172:175], v[188:191], v[8:11]
	v_mfma_f32_16x16x32_bf16 v[20:23], v[164:167], v[196:199], v[20:23]
	v_mfma_f32_16x16x32_bf16 v[4:7], v[172:175], v[196:199], v[4:7]
	v_mfma_f32_16x16x32_bf16 v[16:19], v[164:167], v[204:207], v[16:19]
	v_mfma_f32_16x16x32_bf16 v[0:3], v[172:175], v[204:207], v[0:3]
	v_mfma_f32_16x16x32_bf16 v[28:31], v[168:171], v[184:187], v[28:31]
	v_mfma_f32_16x16x32_bf16 v[12:15], v[176:179], v[184:187], v[12:15]
	v_mfma_f32_16x16x32_bf16 v[24:27], v[168:171], v[192:195], v[24:27]
	v_mfma_f32_16x16x32_bf16 v[8:11], v[176:179], v[192:195], v[8:11]
	v_mfma_f32_16x16x32_bf16 v[20:23], v[168:171], v[200:203], v[20:23]
	v_mfma_f32_16x16x32_bf16 v[4:7], v[176:179], v[200:203], v[4:7]
	v_mfma_f32_16x16x32_bf16 v[16:19], v[168:171], v[208:211], v[16:19]
	v_mfma_f32_16x16x32_bf16 v[0:3], v[176:179], v[208:211], v[0:3]
	s_setprio 0
	s_barrier
	s_add_i32 s56, s56, s31
	v_lshl_add_u64 v[212:213], s[20:21], 0, v[134:135]
	s_mov_b32 m0, s56
	ds_read_b128 v[180:183], v147 offset:16384
	ds_read_b128 v[184:187], v147 offset:17408
	ds_read_b128 v[188:191], v147 offset:18432
	ds_read_b128 v[192:195], v147 offset:19456
	ds_read_b128 v[196:199], v147 offset:20480
	ds_read_b128 v[200:203], v147 offset:21504
	ds_read_b128 v[204:207], v147 offset:22528
	ds_read_b128 v[208:211], v147 offset:23552
	global_load_lds_dwordx4 v[212:213], off
	s_add_i32 m0, s56, 0x2000
	s_add_u32 s56, s20, 0x200000
	v_lshl_add_u64 v[212:213], s[20:21], 0, v[130:131]
	s_addc_u32 s57, s21, 0
	s_add_i32 s58, s58, s31
	global_load_lds_dwordx4 v[212:213], off
	v_lshl_add_u64 v[212:213], s[56:57], 0, v[134:135]
	s_mov_b32 m0, s58
	v_lshl_add_u64 v[214:215], s[22:23], 0, v[132:133]
	global_load_lds_dwordx4 v[212:213], off
	v_lshl_add_u64 v[212:213], s[56:57], 0, v[130:131]
	s_add_i32 m0, s58, 0x2000
	s_nop 0
	global_load_lds_dwordx4 v[212:213], off
	v_lshl_add_u64 v[212:213], s[22:23], 0, v[128:129]
	s_mov_b32 m0, s42
	s_nop 0
	global_load_lds_dwordx4 v[212:213], off
	s_mov_b32 m0, s43
	s_nop 0
	global_load_lds_dwordx4 v[214:215], off
	s_waitcnt vmcnt(8)
	s_waitcnt lgkmcnt(0)
	s_barrier
	s_setprio 1
	s_waitcnt lgkmcnt(0)
	v_mfma_f32_16x16x32_bf16 v[124:127], v[148:151], v[180:183], v[124:127]
	v_mfma_f32_16x16x32_bf16 v[108:111], v[156:159], v[180:183], v[108:111]
	v_mfma_f32_16x16x32_bf16 v[120:123], v[148:151], v[188:191], v[120:123]
	v_mfma_f32_16x16x32_bf16 v[104:107], v[156:159], v[188:191], v[104:107]
	v_mfma_f32_16x16x32_bf16 v[116:119], v[148:151], v[196:199], v[116:119]
	v_mfma_f32_16x16x32_bf16 v[100:103], v[156:159], v[196:199], v[100:103]
	v_mfma_f32_16x16x32_bf16 v[112:115], v[148:151], v[204:207], v[112:115]
	v_mfma_f32_16x16x32_bf16 v[96:99], v[156:159], v[204:207], v[96:99]
	v_mfma_f32_16x16x32_bf16 v[124:127], v[152:155], v[184:187], v[124:127]
	v_mfma_f32_16x16x32_bf16 v[108:111], v[160:163], v[184:187], v[108:111]
	v_mfma_f32_16x16x32_bf16 v[120:123], v[152:155], v[192:195], v[120:123]
	v_mfma_f32_16x16x32_bf16 v[104:107], v[160:163], v[192:195], v[104:107]
	v_mfma_f32_16x16x32_bf16 v[116:119], v[152:155], v[200:203], v[116:119]
	v_mfma_f32_16x16x32_bf16 v[100:103], v[160:163], v[200:203], v[100:103]
	v_mfma_f32_16x16x32_bf16 v[112:115], v[152:155], v[208:211], v[112:115]
	v_mfma_f32_16x16x32_bf16 v[96:99], v[160:163], v[208:211], v[96:99]
	v_mfma_f32_16x16x32_bf16 v[76:79], v[164:167], v[180:183], v[76:79]
	v_mfma_f32_16x16x32_bf16 v[44:47], v[172:175], v[180:183], v[44:47]
	v_mfma_f32_16x16x32_bf16 v[72:75], v[164:167], v[188:191], v[72:75]
	v_mfma_f32_16x16x32_bf16 v[40:43], v[172:175], v[188:191], v[40:43]
	v_mfma_f32_16x16x32_bf16 v[68:71], v[164:167], v[196:199], v[68:71]
	v_mfma_f32_16x16x32_bf16 v[36:39], v[172:175], v[196:199], v[36:39]
	v_mfma_f32_16x16x32_bf16 v[64:67], v[164:167], v[204:207], v[64:67]
	v_mfma_f32_16x16x32_bf16 v[32:35], v[172:175], v[204:207], v[32:35]
	v_mfma_f32_16x16x32_bf16 v[76:79], v[168:171], v[184:187], v[76:79]
	v_mfma_f32_16x16x32_bf16 v[44:47], v[176:179], v[184:187], v[44:47]
	v_mfma_f32_16x16x32_bf16 v[72:75], v[168:171], v[192:195], v[72:75]
	v_mfma_f32_16x16x32_bf16 v[40:43], v[176:179], v[192:195], v[40:43]
	v_mfma_f32_16x16x32_bf16 v[68:71], v[168:171], v[200:203], v[68:71]
	v_mfma_f32_16x16x32_bf16 v[36:39], v[176:179], v[200:203], v[36:39]
	v_mfma_f32_16x16x32_bf16 v[64:67], v[168:171], v[208:211], v[64:67]
	v_mfma_f32_16x16x32_bf16 v[32:35], v[176:179], v[208:211], v[32:35]
	s_setprio 0
	s_barrier
	s_add_i32 s56, 0, 0x18000
	s_add_i32 s57, 0, 0x1c000
	v_add_u32_e32 v160, s56, v146
	v_add_u32_e32 v176, s57, v146
	ds_read_b128 v[148:151], v160
	ds_read_b128 v[152:155], v160 offset:1024
	ds_read_b128 v[156:159], v160 offset:2048
	ds_read_b128 v[160:163], v160 offset:3072
	ds_read_b128 v[164:167], v176
	ds_read_b128 v[168:171], v176 offset:1024
	ds_read_b128 v[172:175], v176 offset:2048
	ds_read_b128 v[176:179], v176 offset:3072
	s_add_u32 s22, s22, 0x200000
	s_addc_u32 s23, s23, 0
	s_mov_b32 m0, s44
	v_lshl_add_u64 v[216:217], s[22:23], 0, v[128:129]
	ds_read_b128 v[180:183], v147 offset:32768
	ds_read_b128 v[184:187], v147 offset:33792
	ds_read_b128 v[188:191], v147 offset:34816
	ds_read_b128 v[192:195], v147 offset:35840
	ds_read_b128 v[196:199], v147 offset:36864
	ds_read_b128 v[200:203], v147 offset:37888
	ds_read_b128 v[204:207], v147 offset:38912
	ds_read_b128 v[208:211], v147 offset:39936
	global_load_lds_dwordx4 v[216:217], off
	v_lshl_add_u64 v[216:217], s[22:23], 0, v[132:133]
	s_mov_b32 m0, s45
	s_nop 0
	global_load_lds_dwordx4 v[216:217], off
	s_waitcnt vmcnt(8)
	s_waitcnt lgkmcnt(0)
	s_barrier
	s_setprio 1
	s_waitcnt lgkmcnt(0)
	v_mfma_f32_16x16x32_bf16 v[92:95], v[148:151], v[180:183], v[92:95]
	v_mfma_f32_16x16x32_bf16 v[60:63], v[156:159], v[180:183], v[60:63]
	v_mfma_f32_16x16x32_bf16 v[88:91], v[148:151], v[188:191], v[88:91]
	v_mfma_f32_16x16x32_bf16 v[56:59], v[156:159], v[188:191], v[56:59]
	v_mfma_f32_16x16x32_bf16 v[84:87], v[148:151], v[196:199], v[84:87]
	v_mfma_f32_16x16x32_bf16 v[52:55], v[156:159], v[196:199], v[52:55]
	v_mfma_f32_16x16x32_bf16 v[80:83], v[148:151], v[204:207], v[80:83]
	v_mfma_f32_16x16x32_bf16 v[48:51], v[156:159], v[204:207], v[48:51]
	v_mfma_f32_16x16x32_bf16 v[92:95], v[152:155], v[184:187], v[92:95]
	v_mfma_f32_16x16x32_bf16 v[60:63], v[160:163], v[184:187], v[60:63]
	v_mfma_f32_16x16x32_bf16 v[88:91], v[152:155], v[192:195], v[88:91]
	v_mfma_f32_16x16x32_bf16 v[56:59], v[160:163], v[192:195], v[56:59]
	v_mfma_f32_16x16x32_bf16 v[84:87], v[152:155], v[200:203], v[84:87]
	v_mfma_f32_16x16x32_bf16 v[52:55], v[160:163], v[200:203], v[52:55]
	v_mfma_f32_16x16x32_bf16 v[80:83], v[152:155], v[208:211], v[80:83]
	v_mfma_f32_16x16x32_bf16 v[48:51], v[160:163], v[208:211], v[48:51]
	v_mfma_f32_16x16x32_bf16 v[28:31], v[164:167], v[180:183], v[28:31]
	v_mfma_f32_16x16x32_bf16 v[12:15], v[172:175], v[180:183], v[12:15]
	v_mfma_f32_16x16x32_bf16 v[24:27], v[164:167], v[188:191], v[24:27]
	v_mfma_f32_16x16x32_bf16 v[8:11], v[172:175], v[188:191], v[8:11]
	v_mfma_f32_16x16x32_bf16 v[20:23], v[164:167], v[196:199], v[20:23]
	v_mfma_f32_16x16x32_bf16 v[4:7], v[172:175], v[196:199], v[4:7]
	v_mfma_f32_16x16x32_bf16 v[16:19], v[164:167], v[204:207], v[16:19]
	v_mfma_f32_16x16x32_bf16 v[0:3], v[172:175], v[204:207], v[0:3]
	v_mfma_f32_16x16x32_bf16 v[28:31], v[168:171], v[184:187], v[28:31]
	v_mfma_f32_16x16x32_bf16 v[12:15], v[176:179], v[184:187], v[12:15]
	v_mfma_f32_16x16x32_bf16 v[24:27], v[168:171], v[192:195], v[24:27]
	v_mfma_f32_16x16x32_bf16 v[8:11], v[176:179], v[192:195], v[8:11]
	v_mfma_f32_16x16x32_bf16 v[20:23], v[168:171], v[200:203], v[20:23]
	v_mfma_f32_16x16x32_bf16 v[4:7], v[176:179], v[200:203], v[4:7]
	v_mfma_f32_16x16x32_bf16 v[16:19], v[168:171], v[208:211], v[16:19]
	v_mfma_f32_16x16x32_bf16 v[0:3], v[176:179], v[208:211], v[0:3]
	s_setprio 0
	s_barrier
	s_add_u32 s22, s20, 0x4000
	s_addc_u32 s23, s21, 0
	s_add_i32 s56, s56, s31
	v_lshl_add_u64 v[216:217], s[22:23], 0, v[134:135]
	s_mov_b32 m0, s56
	ds_read_b128 v[180:183], v147 offset:49152
	ds_read_b128 v[184:187], v147 offset:50176
	ds_read_b128 v[188:191], v147 offset:51200
	ds_read_b128 v[192:195], v147 offset:52224
	ds_read_b128 v[196:199], v147 offset:53248
	ds_read_b128 v[200:203], v147 offset:54272
	ds_read_b128 v[204:207], v147 offset:55296
	ds_read_b128 v[208:211], v147 offset:56320
	global_load_lds_dwordx4 v[216:217], off
	s_add_i32 m0, s56, 0x2000
	s_add_u32 s20, s20, 0x204000
	v_lshl_add_u64 v[216:217], s[22:23], 0, v[130:131]
	s_addc_u32 s21, s21, 0
	s_add_i32 s22, s57, s31
	global_load_lds_dwordx4 v[216:217], off
	v_lshl_add_u64 v[216:217], s[20:21], 0, v[134:135]
	s_mov_b32 m0, s22
	v_lshl_add_u64 v[212:213], v[212:213], 0, s[34:35]
	global_load_lds_dwordx4 v[216:217], off
	v_lshl_add_u64 v[216:217], s[20:21], 0, v[130:131]
	s_add_i32 m0, s22, 0x2000
	s_nop 0
	global_load_lds_dwordx4 v[216:217], off
	s_mov_b32 m0, s47
	s_nop 0
	global_load_lds_dwordx4 v[212:213], off
	v_lshl_add_u64 v[212:213], v[214:215], 0, s[34:35]
	s_mov_b32 m0, s48
	s_nop 0
	global_load_lds_dwordx4 v[212:213], off
	s_waitcnt vmcnt(8)
	s_waitcnt lgkmcnt(0)
	s_barrier
	s_setprio 1
	s_waitcnt lgkmcnt(0)
	v_mfma_f32_16x16x32_bf16 v[124:127], v[148:151], v[180:183], v[124:127]
	v_mfma_f32_16x16x32_bf16 v[108:111], v[156:159], v[180:183], v[108:111]
	v_mfma_f32_16x16x32_bf16 v[120:123], v[148:151], v[188:191], v[120:123]
	v_mfma_f32_16x16x32_bf16 v[104:107], v[156:159], v[188:191], v[104:107]
	v_mfma_f32_16x16x32_bf16 v[116:119], v[148:151], v[196:199], v[116:119]
	v_mfma_f32_16x16x32_bf16 v[100:103], v[156:159], v[196:199], v[100:103]
	v_mfma_f32_16x16x32_bf16 v[112:115], v[148:151], v[204:207], v[112:115]
	v_mfma_f32_16x16x32_bf16 v[96:99], v[156:159], v[204:207], v[96:99]
	v_mfma_f32_16x16x32_bf16 v[124:127], v[152:155], v[184:187], v[124:127]
	v_mfma_f32_16x16x32_bf16 v[108:111], v[160:163], v[184:187], v[108:111]
	v_mfma_f32_16x16x32_bf16 v[120:123], v[152:155], v[192:195], v[120:123]
	v_mfma_f32_16x16x32_bf16 v[104:107], v[160:163], v[192:195], v[104:107]
	v_mfma_f32_16x16x32_bf16 v[116:119], v[152:155], v[200:203], v[116:119]
	v_mfma_f32_16x16x32_bf16 v[100:103], v[160:163], v[200:203], v[100:103]
	v_mfma_f32_16x16x32_bf16 v[112:115], v[152:155], v[208:211], v[112:115]
	v_mfma_f32_16x16x32_bf16 v[96:99], v[160:163], v[208:211], v[96:99]
	v_mfma_f32_16x16x32_bf16 v[76:79], v[164:167], v[180:183], v[76:79]
	v_mfma_f32_16x16x32_bf16 v[44:47], v[172:175], v[180:183], v[44:47]
	v_mfma_f32_16x16x32_bf16 v[72:75], v[164:167], v[188:191], v[72:75]
	v_mfma_f32_16x16x32_bf16 v[40:43], v[172:175], v[188:191], v[40:43]
	v_mfma_f32_16x16x32_bf16 v[68:71], v[164:167], v[196:199], v[68:71]
	v_mfma_f32_16x16x32_bf16 v[36:39], v[172:175], v[196:199], v[36:39]
	v_mfma_f32_16x16x32_bf16 v[64:67], v[164:167], v[204:207], v[64:67]
	v_mfma_f32_16x16x32_bf16 v[32:35], v[172:175], v[204:207], v[32:35]
	v_mfma_f32_16x16x32_bf16 v[76:79], v[168:171], v[184:187], v[76:79]
	v_mfma_f32_16x16x32_bf16 v[44:47], v[176:179], v[184:187], v[44:47]
	v_mfma_f32_16x16x32_bf16 v[72:75], v[168:171], v[192:195], v[72:75]
	v_mfma_f32_16x16x32_bf16 v[40:43], v[176:179], v[192:195], v[40:43]
	v_mfma_f32_16x16x32_bf16 v[68:71], v[168:171], v[200:203], v[68:71]
	v_mfma_f32_16x16x32_bf16 v[36:39], v[176:179], v[200:203], v[36:39]
	v_mfma_f32_16x16x32_bf16 v[64:67], v[168:171], v[208:211], v[64:67]
	v_mfma_f32_16x16x32_bf16 v[32:35], v[176:179], v[208:211], v[32:35]
	s_setprio 0
	s_barrier
	s_add_i32 s55, s55, 2
	s_add_u32 s53, s53, 0x8000
	s_addc_u32 s54, s54, 0
	s_add_u32 s18, s18, 0x100
	s_addc_u32 s19, s19, 0
	v_lshl_add_u64 v[142:143], v[142:143], 0, s[12:13]
	s_cmpk_gt_u32 s55, 0x7d
	v_lshl_add_u64 v[140:141], v[140:141], 0, s[12:13]
	s_cbranch_scc0 .LBB0_41
	s_andn2_b64 vcc, exec, s[40:41]
	s_cbranch_vccnz .LBB0_33
	v_mov_b32_e32 v32, 0
	s_mov_b32 s6, s10
	s_mov_b32 s27, s36
	s_mov_b64 s[4:5], s[16:17]
	s_mov_b64 s[8:9], s[14:15]
	s_mov_b32 s49, s50
	v_mov_b32_e32 v33, v32
	v_mov_b32_e32 v34, v32
	v_mov_b32_e32 v35, v32
	v_mov_b32_e32 v64, v32
	v_mov_b32_e32 v65, v32
	v_mov_b32_e32 v66, v32
	v_mov_b32_e32 v67, v32
	v_mov_b32_e32 v36, v32
	v_mov_b32_e32 v37, v32
	v_mov_b32_e32 v38, v32
	v_mov_b32_e32 v39, v32
	v_mov_b32_e32 v68, v32
	v_mov_b32_e32 v69, v32
	v_mov_b32_e32 v70, v32
	v_mov_b32_e32 v71, v32
	v_mov_b32_e32 v40, v32
	v_mov_b32_e32 v41, v32
	v_mov_b32_e32 v42, v32
	v_mov_b32_e32 v43, v32
	v_mov_b32_e32 v72, v32
	v_mov_b32_e32 v73, v32
	v_mov_b32_e32 v74, v32
	v_mov_b32_e32 v75, v32
	v_mov_b32_e32 v44, v32
	v_mov_b32_e32 v45, v32
	v_mov_b32_e32 v46, v32
	v_mov_b32_e32 v47, v32
	v_mov_b32_e32 v76, v32
	v_mov_b32_e32 v77, v32
	v_mov_b32_e32 v78, v32
	v_mov_b32_e32 v79, v32
	v_mov_b32_e32 v96, v32
	v_mov_b32_e32 v97, v32
	v_mov_b32_e32 v98, v32
	v_mov_b32_e32 v99, v32
	v_mov_b32_e32 v112, v32
	v_mov_b32_e32 v113, v32
	v_mov_b32_e32 v114, v32
	v_mov_b32_e32 v115, v32
	v_mov_b32_e32 v100, v32
	v_mov_b32_e32 v101, v32
	v_mov_b32_e32 v102, v32
	v_mov_b32_e32 v103, v32
	v_mov_b32_e32 v116, v32
	v_mov_b32_e32 v117, v32
	v_mov_b32_e32 v118, v32
	v_mov_b32_e32 v119, v32
	v_mov_b32_e32 v104, v32
	v_mov_b32_e32 v105, v32
	v_mov_b32_e32 v106, v32
	v_mov_b32_e32 v107, v32
	v_mov_b32_e32 v120, v32
	v_mov_b32_e32 v121, v32
	v_mov_b32_e32 v122, v32
	v_mov_b32_e32 v123, v32
	v_mov_b32_e32 v108, v32
	v_mov_b32_e32 v109, v32
	v_mov_b32_e32 v110, v32
	v_mov_b32_e32 v111, v32
	v_mov_b32_e32 v124, v32
	v_mov_b32_e32 v125, v32
	v_mov_b32_e32 v126, v32
	v_mov_b32_e32 v127, v32
	v_mov_b32_e32 v0, v32
	v_mov_b32_e32 v1, v32
	v_mov_b32_e32 v2, v32
	v_mov_b32_e32 v3, v32
	v_mov_b32_e32 v16, v32
	v_mov_b32_e32 v17, v32
	v_mov_b32_e32 v18, v32
	v_mov_b32_e32 v19, v32
	v_mov_b32_e32 v4, v32
	v_mov_b32_e32 v5, v32
	v_mov_b32_e32 v6, v32
	v_mov_b32_e32 v7, v32
	v_mov_b32_e32 v20, v32
	v_mov_b32_e32 v21, v32
	v_mov_b32_e32 v22, v32
	v_mov_b32_e32 v23, v32
	v_mov_b32_e32 v8, v32
	v_mov_b32_e32 v9, v32
	v_mov_b32_e32 v10, v32
	v_mov_b32_e32 v11, v32
	v_mov_b32_e32 v24, v32
	v_mov_b32_e32 v25, v32
	v_mov_b32_e32 v26, v32
	v_mov_b32_e32 v27, v32
	v_mov_b32_e32 v12, v32
	v_mov_b32_e32 v13, v32
	v_mov_b32_e32 v14, v32
	v_mov_b32_e32 v15, v32
	v_mov_b32_e32 v28, v32
	v_mov_b32_e32 v29, v32
	v_mov_b32_e32 v30, v32
	v_mov_b32_e32 v31, v32
	v_mov_b32_e32 v48, v32
	v_mov_b32_e32 v49, v32
	v_mov_b32_e32 v50, v32
	v_mov_b32_e32 v51, v32
	v_mov_b32_e32 v80, v32
	v_mov_b32_e32 v81, v32
	v_mov_b32_e32 v82, v32
	v_mov_b32_e32 v83, v32
	v_mov_b32_e32 v52, v32
	v_mov_b32_e32 v53, v32
	v_mov_b32_e32 v54, v32
	v_mov_b32_e32 v55, v32
	v_mov_b32_e32 v84, v32
	v_mov_b32_e32 v85, v32
	v_mov_b32_e32 v86, v32
	v_mov_b32_e32 v87, v32
	v_mov_b32_e32 v56, v32
	v_mov_b32_e32 v57, v32
	v_mov_b32_e32 v58, v32
	v_mov_b32_e32 v59, v32
	v_mov_b32_e32 v88, v32
	v_mov_b32_e32 v89, v32
	v_mov_b32_e32 v90, v32
	v_mov_b32_e32 v91, v32
	v_mov_b32_e32 v60, v32
	v_mov_b32_e32 v61, v32
	v_mov_b32_e32 v62, v32
	v_mov_b32_e32 v63, v32
	v_mov_b32_e32 v92, v32
	v_mov_b32_e32 v93, v32
	v_mov_b32_e32 v94, v32
	v_mov_b32_e32 v95, v32
	s_branch .LBB0_33

.LBB0_101:
	s_add_u32 s16, s14, 0xfff80080
	s_addc_u32 s17, s15, -1
	s_add_i32 s49, 0, 0x10000
	s_cmp_eq_u32 s48, 28
	s_cselect_b32 s19, s11, s17
	s_cselect_b32 s18, s44, s16
	v_add_u32_e32 v144, s49, v147
	s_cselect_b32 s17, s9, s47
	s_cselect_b32 s16, s45, s46
	s_add_i32 s52, 0, 0x14000
	ds_read_b128 v[140:143], v144
	ds_read_b128 v[150:153], v144 offset:1024
	ds_read_b128 v[154:157], v144 offset:2048
	ds_read_b128 v[158:161], v144 offset:3072
	v_add_u32_e32 v144, s52, v147
	ds_read_b128 v[162:165], v144
	ds_read_b128 v[166:169], v144 offset:1024
	ds_read_b128 v[170:173], v144 offset:2048
	ds_read_b128 v[174:177], v144 offset:3072
	v_lshl_add_u64 v[144:145], s[14:15], 0, v[138:139]
	s_add_i32 m0, s23, 0xc000
	ds_read_b128 v[178:181], v149
	ds_read_b128 v[182:185], v149 offset:1024
	ds_read_b128 v[186:189], v149 offset:2048
	ds_read_b128 v[190:193], v149 offset:3072
	ds_read_b128 v[194:197], v149 offset:4096
	ds_read_b128 v[198:201], v149 offset:5120
	ds_read_b128 v[202:205], v149 offset:6144
	ds_read_b128 v[206:209], v149 offset:7168
	global_load_lds_dwordx4 v[144:145], off
	v_lshl_add_u64 v[144:145], s[14:15], 0, v[136:137]
	s_add_i32 m0, s23, 0xe000
	s_nop 0
	global_load_lds_dwordx4 v[144:145], off
	s_waitcnt vmcnt(8)
	s_waitcnt lgkmcnt(0)
	s_barrier
	s_setprio 1
	s_waitcnt lgkmcnt(0)
	v_mfma_f32_16x16x32_bf16 v[124:127], v[140:143], v[178:181], v[124:127]
	v_mfma_f32_16x16x32_bf16 v[120:123], v[154:157], v[178:181], v[120:123]
	v_mfma_f32_16x16x32_bf16 v[108:111], v[140:143], v[186:189], v[108:111]
	v_mfma_f32_16x16x32_bf16 v[104:107], v[154:157], v[186:189], v[104:107]
	v_mfma_f32_16x16x32_bf16 v[92:95], v[140:143], v[194:197], v[92:95]
	v_mfma_f32_16x16x32_bf16 v[88:91], v[154:157], v[194:197], v[88:91]
	v_mfma_f32_16x16x32_bf16 v[76:79], v[140:143], v[202:205], v[76:79]
	v_mfma_f32_16x16x32_bf16 v[72:75], v[154:157], v[202:205], v[72:75]
	v_mfma_f32_16x16x32_bf16 v[124:127], v[150:153], v[182:185], v[124:127]
	v_mfma_f32_16x16x32_bf16 v[120:123], v[158:161], v[182:185], v[120:123]
	v_mfma_f32_16x16x32_bf16 v[108:111], v[150:153], v[190:193], v[108:111]
	v_mfma_f32_16x16x32_bf16 v[104:107], v[158:161], v[190:193], v[104:107]
	v_mfma_f32_16x16x32_bf16 v[92:95], v[150:153], v[198:201], v[92:95]
	v_mfma_f32_16x16x32_bf16 v[88:91], v[158:161], v[198:201], v[88:91]
	v_mfma_f32_16x16x32_bf16 v[76:79], v[150:153], v[206:209], v[76:79]
	v_mfma_f32_16x16x32_bf16 v[72:75], v[158:161], v[206:209], v[72:75]
	v_mfma_f32_16x16x32_bf16 v[116:119], v[162:165], v[178:181], v[116:119]
	v_mfma_f32_16x16x32_bf16 v[112:115], v[170:173], v[178:181], v[112:115]
	v_mfma_f32_16x16x32_bf16 v[100:103], v[162:165], v[186:189], v[100:103]
	v_mfma_f32_16x16x32_bf16 v[96:99], v[170:173], v[186:189], v[96:99]
	v_mfma_f32_16x16x32_bf16 v[84:87], v[162:165], v[194:197], v[84:87]
	v_mfma_f32_16x16x32_bf16 v[80:83], v[170:173], v[194:197], v[80:83]
	v_mfma_f32_16x16x32_bf16 v[68:71], v[162:165], v[202:205], v[68:71]
	v_mfma_f32_16x16x32_bf16 v[64:67], v[170:173], v[202:205], v[64:67]
	v_mfma_f32_16x16x32_bf16 v[116:119], v[166:169], v[182:185], v[116:119]
	v_mfma_f32_16x16x32_bf16 v[112:115], v[174:177], v[182:185], v[112:115]
	v_mfma_f32_16x16x32_bf16 v[100:103], v[166:169], v[190:193], v[100:103]
	v_mfma_f32_16x16x32_bf16 v[96:99], v[174:177], v[190:193], v[96:99]
	v_mfma_f32_16x16x32_bf16 v[84:87], v[166:169], v[198:201], v[84:87]
	v_mfma_f32_16x16x32_bf16 v[80:83], v[174:177], v[198:201], v[80:83]
	v_mfma_f32_16x16x32_bf16 v[68:71], v[166:169], v[206:209], v[68:71]
	v_mfma_f32_16x16x32_bf16 v[64:67], v[174:177], v[206:209], v[64:67]
	s_setprio 0
	s_barrier
	s_add_i32 s49, s49, s22
	v_lshl_add_u64 v[144:145], s[16:17], 0, v[134:135]
	s_mov_b32 m0, s49
	ds_read_b128 v[178:181], v149 offset:16384
	ds_read_b128 v[182:185], v149 offset:17408
	ds_read_b128 v[186:189], v149 offset:18432
	ds_read_b128 v[190:193], v149 offset:19456
	ds_read_b128 v[194:197], v149 offset:20480
	ds_read_b128 v[198:201], v149 offset:21504
	ds_read_b128 v[202:205], v149 offset:22528
	ds_read_b128 v[206:209], v149 offset:23552
	global_load_lds_dwordx4 v[144:145], off
	s_add_i32 m0, s49, 0x2000
	s_add_u32 s50, s16, 0x80000
	v_lshl_add_u64 v[144:145], s[16:17], 0, v[130:131]
	s_addc_u32 s51, s17, 0
	s_add_i32 s49, s52, s22
	global_load_lds_dwordx4 v[144:145], off
	v_lshl_add_u64 v[144:145], s[50:51], 0, v[134:135]
	s_mov_b32 m0, s49
	v_lshl_add_u64 v[210:211], s[18:19], 0, v[132:133]
	global_load_lds_dwordx4 v[144:145], off
	v_lshl_add_u64 v[144:145], s[50:51], 0, v[130:131]
	s_add_i32 m0, s49, 0x2000
	s_nop 0
	global_load_lds_dwordx4 v[144:145], off
	v_lshl_add_u64 v[144:145], s[18:19], 0, v[128:129]
	s_mov_b32 m0, s23
	s_nop 0
	global_load_lds_dwordx4 v[144:145], off
	s_mov_b32 m0, s24
	s_nop 0
	global_load_lds_dwordx4 v[210:211], off
	s_waitcnt vmcnt(8)
	s_waitcnt lgkmcnt(0)
	s_barrier
	s_setprio 1
	s_waitcnt lgkmcnt(0)
	v_mfma_f32_16x16x32_bf16 v[60:63], v[140:143], v[178:181], v[60:63]
	v_mfma_f32_16x16x32_bf16 v[56:59], v[154:157], v[178:181], v[56:59]
	v_mfma_f32_16x16x32_bf16 v[44:47], v[140:143], v[186:189], v[44:47]
	v_mfma_f32_16x16x32_bf16 v[40:43], v[154:157], v[186:189], v[40:43]
	v_mfma_f32_16x16x32_bf16 v[28:31], v[140:143], v[194:197], v[28:31]
	v_mfma_f32_16x16x32_bf16 v[24:27], v[154:157], v[194:197], v[24:27]
	v_mfma_f32_16x16x32_bf16 v[12:15], v[140:143], v[202:205], v[12:15]
	v_mfma_f32_16x16x32_bf16 v[8:11], v[154:157], v[202:205], v[8:11]
	v_mfma_f32_16x16x32_bf16 v[60:63], v[150:153], v[182:185], v[60:63]
	v_mfma_f32_16x16x32_bf16 v[56:59], v[158:161], v[182:185], v[56:59]
	v_mfma_f32_16x16x32_bf16 v[44:47], v[150:153], v[190:193], v[44:47]
	v_mfma_f32_16x16x32_bf16 v[40:43], v[158:161], v[190:193], v[40:43]
	v_mfma_f32_16x16x32_bf16 v[28:31], v[150:153], v[198:201], v[28:31]
	v_mfma_f32_16x16x32_bf16 v[24:27], v[158:161], v[198:201], v[24:27]
	v_mfma_f32_16x16x32_bf16 v[12:15], v[150:153], v[206:209], v[12:15]
	v_mfma_f32_16x16x32_bf16 v[8:11], v[158:161], v[206:209], v[8:11]
	v_mfma_f32_16x16x32_bf16 v[52:55], v[162:165], v[178:181], v[52:55]
	v_mfma_f32_16x16x32_bf16 v[48:51], v[170:173], v[178:181], v[48:51]
	v_mfma_f32_16x16x32_bf16 v[36:39], v[162:165], v[186:189], v[36:39]
	v_mfma_f32_16x16x32_bf16 v[32:35], v[170:173], v[186:189], v[32:35]
	v_mfma_f32_16x16x32_bf16 v[20:23], v[162:165], v[194:197], v[20:23]
	v_mfma_f32_16x16x32_bf16 v[16:19], v[170:173], v[194:197], v[16:19]
	v_mfma_f32_16x16x32_bf16 v[4:7], v[162:165], v[202:205], v[4:7]
	v_mfma_f32_16x16x32_bf16 v[0:3], v[170:173], v[202:205], v[0:3]
	v_mfma_f32_16x16x32_bf16 v[52:55], v[166:169], v[182:185], v[52:55]
	v_mfma_f32_16x16x32_bf16 v[48:51], v[174:177], v[182:185], v[48:51]
	v_mfma_f32_16x16x32_bf16 v[36:39], v[166:169], v[190:193], v[36:39]
	v_mfma_f32_16x16x32_bf16 v[32:35], v[174:177], v[190:193], v[32:35]
	v_mfma_f32_16x16x32_bf16 v[20:23], v[166:169], v[198:201], v[20:23]
	v_mfma_f32_16x16x32_bf16 v[16:19], v[174:177], v[198:201], v[16:19]
	v_mfma_f32_16x16x32_bf16 v[4:7], v[166:169], v[206:209], v[4:7]
	v_mfma_f32_16x16x32_bf16 v[0:3], v[174:177], v[206:209], v[0:3]
	s_setprio 0
	s_barrier
	s_add_i32 s49, 0, 0x18000
	s_add_i32 s50, 0, 0x1c000
	v_add_u32_e32 v158, s49, v147
	v_add_u32_e32 v174, s50, v147
	ds_read_b128 v[140:143], v158
	ds_read_b128 v[150:153], v158 offset:1024
	ds_read_b128 v[154:157], v158 offset:2048
	ds_read_b128 v[158:161], v158 offset:3072
	ds_read_b128 v[162:165], v174
	ds_read_b128 v[166:169], v174 offset:1024
	ds_read_b128 v[170:173], v174 offset:2048
	ds_read_b128 v[174:177], v174 offset:3072
	s_add_u32 s18, s18, 0x80000
	s_addc_u32 s19, s19, 0
	s_mov_b32 m0, s25
	v_lshl_add_u64 v[212:213], s[18:19], 0, v[128:129]
	ds_read_b128 v[178:181], v149 offset:32768
	ds_read_b128 v[182:185], v149 offset:33792
	ds_read_b128 v[186:189], v149 offset:34816
	ds_read_b128 v[190:193], v149 offset:35840
	ds_read_b128 v[194:197], v149 offset:36864
	ds_read_b128 v[198:201], v149 offset:37888
	ds_read_b128 v[202:205], v149 offset:38912
	ds_read_b128 v[206:209], v149 offset:39936
	global_load_lds_dwordx4 v[212:213], off
	v_lshl_add_u64 v[212:213], s[18:19], 0, v[132:133]
	s_mov_b32 m0, s26
	s_nop 0
	global_load_lds_dwordx4 v[212:213], off
	s_waitcnt vmcnt(8)
	s_waitcnt lgkmcnt(0)
	s_barrier
	s_setprio 1
	s_waitcnt lgkmcnt(0)
	v_mfma_f32_16x16x32_bf16 v[124:127], v[140:143], v[178:181], v[124:127]
	v_mfma_f32_16x16x32_bf16 v[120:123], v[154:157], v[178:181], v[120:123]
	v_mfma_f32_16x16x32_bf16 v[108:111], v[140:143], v[186:189], v[108:111]
	v_mfma_f32_16x16x32_bf16 v[104:107], v[154:157], v[186:189], v[104:107]
	v_mfma_f32_16x16x32_bf16 v[92:95], v[140:143], v[194:197], v[92:95]
	v_mfma_f32_16x16x32_bf16 v[88:91], v[154:157], v[194:197], v[88:91]
	v_mfma_f32_16x16x32_bf16 v[76:79], v[140:143], v[202:205], v[76:79]
	v_mfma_f32_16x16x32_bf16 v[72:75], v[154:157], v[202:205], v[72:75]
	v_mfma_f32_16x16x32_bf16 v[124:127], v[150:153], v[182:185], v[124:127]
	v_mfma_f32_16x16x32_bf16 v[120:123], v[158:161], v[182:185], v[120:123]
	v_mfma_f32_16x16x32_bf16 v[108:111], v[150:153], v[190:193], v[108:111]
	v_mfma_f32_16x16x32_bf16 v[104:107], v[158:161], v[190:193], v[104:107]
	v_mfma_f32_16x16x32_bf16 v[92:95], v[150:153], v[198:201], v[92:95]
	v_mfma_f32_16x16x32_bf16 v[88:91], v[158:161], v[198:201], v[88:91]
	v_mfma_f32_16x16x32_bf16 v[76:79], v[150:153], v[206:209], v[76:79]
	v_mfma_f32_16x16x32_bf16 v[72:75], v[158:161], v[206:209], v[72:75]
	v_mfma_f32_16x16x32_bf16 v[116:119], v[162:165], v[178:181], v[116:119]
	v_mfma_f32_16x16x32_bf16 v[112:115], v[170:173], v[178:181], v[112:115]
	v_mfma_f32_16x16x32_bf16 v[100:103], v[162:165], v[186:189], v[100:103]
	v_mfma_f32_16x16x32_bf16 v[96:99], v[170:173], v[186:189], v[96:99]
	v_mfma_f32_16x16x32_bf16 v[84:87], v[162:165], v[194:197], v[84:87]
	v_mfma_f32_16x16x32_bf16 v[80:83], v[170:173], v[194:197], v[80:83]
	v_mfma_f32_16x16x32_bf16 v[68:71], v[162:165], v[202:205], v[68:71]
	v_mfma_f32_16x16x32_bf16 v[64:67], v[170:173], v[202:205], v[64:67]
	v_mfma_f32_16x16x32_bf16 v[116:119], v[166:169], v[182:185], v[116:119]
	v_mfma_f32_16x16x32_bf16 v[112:115], v[174:177], v[182:185], v[112:115]
	v_mfma_f32_16x16x32_bf16 v[100:103], v[166:169], v[190:193], v[100:103]
	v_mfma_f32_16x16x32_bf16 v[96:99], v[174:177], v[190:193], v[96:99]
	v_mfma_f32_16x16x32_bf16 v[84:87], v[166:169], v[198:201], v[84:87]
	v_mfma_f32_16x16x32_bf16 v[80:83], v[174:177], v[198:201], v[80:83]
	v_mfma_f32_16x16x32_bf16 v[68:71], v[166:169], v[206:209], v[68:71]
	v_mfma_f32_16x16x32_bf16 v[64:67], v[174:177], v[206:209], v[64:67]
	s_setprio 0
	s_barrier
	s_add_u32 s18, s16, 0x4000
	s_addc_u32 s19, s17, 0
	s_add_i32 s49, s49, s22
	v_lshl_add_u64 v[212:213], s[18:19], 0, v[134:135]
	s_mov_b32 m0, s49
	ds_read_b128 v[178:181], v149 offset:49152
	ds_read_b128 v[182:185], v149 offset:50176
	ds_read_b128 v[186:189], v149 offset:51200
	ds_read_b128 v[190:193], v149 offset:52224
	ds_read_b128 v[194:197], v149 offset:53248
	ds_read_b128 v[198:201], v149 offset:54272
	ds_read_b128 v[202:205], v149 offset:55296
	ds_read_b128 v[206:209], v149 offset:56320
	global_load_lds_dwordx4 v[212:213], off
	s_add_i32 m0, s49, 0x2000
	s_add_u32 s16, s16, 0x84000
	v_lshl_add_u64 v[212:213], s[18:19], 0, v[130:131]
	s_addc_u32 s17, s17, 0
	s_add_i32 s18, s50, s22
	global_load_lds_dwordx4 v[212:213], off
	v_lshl_add_u64 v[212:213], s[16:17], 0, v[134:135]
	s_mov_b32 m0, s18
	v_lshl_add_u64 v[144:145], v[144:145], 0, s[34:35]
	global_load_lds_dwordx4 v[212:213], off
	v_lshl_add_u64 v[212:213], s[16:17], 0, v[130:131]
	s_add_i32 m0, s18, 0x2000
	s_nop 0
	global_load_lds_dwordx4 v[212:213], off
	s_mov_b32 m0, s28
	s_nop 0
	global_load_lds_dwordx4 v[144:145], off
	v_lshl_add_u64 v[144:145], v[210:211], 0, s[34:35]
	s_mov_b32 m0, s29
	s_nop 0
	global_load_lds_dwordx4 v[144:145], off
	s_waitcnt vmcnt(8)
	s_waitcnt lgkmcnt(0)
	s_barrier
	s_setprio 1
	s_waitcnt lgkmcnt(0)
	v_mfma_f32_16x16x32_bf16 v[60:63], v[140:143], v[178:181], v[60:63]
	v_mfma_f32_16x16x32_bf16 v[56:59], v[154:157], v[178:181], v[56:59]
	v_mfma_f32_16x16x32_bf16 v[44:47], v[140:143], v[186:189], v[44:47]
	v_mfma_f32_16x16x32_bf16 v[40:43], v[154:157], v[186:189], v[40:43]
	v_mfma_f32_16x16x32_bf16 v[28:31], v[140:143], v[194:197], v[28:31]
	v_mfma_f32_16x16x32_bf16 v[24:27], v[154:157], v[194:197], v[24:27]
	v_mfma_f32_16x16x32_bf16 v[12:15], v[140:143], v[202:205], v[12:15]
	v_mfma_f32_16x16x32_bf16 v[8:11], v[154:157], v[202:205], v[8:11]
	v_mfma_f32_16x16x32_bf16 v[60:63], v[150:153], v[182:185], v[60:63]
	v_mfma_f32_16x16x32_bf16 v[56:59], v[158:161], v[182:185], v[56:59]
	v_mfma_f32_16x16x32_bf16 v[44:47], v[150:153], v[190:193], v[44:47]
	v_mfma_f32_16x16x32_bf16 v[40:43], v[158:161], v[190:193], v[40:43]
	v_mfma_f32_16x16x32_bf16 v[28:31], v[150:153], v[198:201], v[28:31]
	v_mfma_f32_16x16x32_bf16 v[24:27], v[158:161], v[198:201], v[24:27]
	v_mfma_f32_16x16x32_bf16 v[12:15], v[150:153], v[206:209], v[12:15]
	v_mfma_f32_16x16x32_bf16 v[8:11], v[158:161], v[206:209], v[8:11]
	v_mfma_f32_16x16x32_bf16 v[52:55], v[162:165], v[178:181], v[52:55]
	v_mfma_f32_16x16x32_bf16 v[48:51], v[170:173], v[178:181], v[48:51]
	v_mfma_f32_16x16x32_bf16 v[36:39], v[162:165], v[186:189], v[36:39]
	v_mfma_f32_16x16x32_bf16 v[32:35], v[170:173], v[186:189], v[32:35]
	v_mfma_f32_16x16x32_bf16 v[20:23], v[162:165], v[194:197], v[20:23]
	v_mfma_f32_16x16x32_bf16 v[16:19], v[170:173], v[194:197], v[16:19]
	v_mfma_f32_16x16x32_bf16 v[4:7], v[162:165], v[202:205], v[4:7]
	v_mfma_f32_16x16x32_bf16 v[0:3], v[170:173], v[202:205], v[0:3]
	v_mfma_f32_16x16x32_bf16 v[52:55], v[166:169], v[182:185], v[52:55]
	v_mfma_f32_16x16x32_bf16 v[48:51], v[174:177], v[182:185], v[48:51]
	v_mfma_f32_16x16x32_bf16 v[36:39], v[166:169], v[190:193], v[36:39]
	v_mfma_f32_16x16x32_bf16 v[32:35], v[174:177], v[190:193], v[32:35]
	v_mfma_f32_16x16x32_bf16 v[20:23], v[166:169], v[198:201], v[20:23]
	v_mfma_f32_16x16x32_bf16 v[16:19], v[174:177], v[198:201], v[16:19]
	v_mfma_f32_16x16x32_bf16 v[4:7], v[166:169], v[206:209], v[4:7]
	v_mfma_f32_16x16x32_bf16 v[0:3], v[174:177], v[206:209], v[0:3]
	s_setprio 0
	s_barrier
	s_add_i32 s48, s48, 2
	s_add_u32 s46, s46, 0x8000
	s_addc_u32 s47, s47, 0
	s_add_u32 s14, s14, 0x100
	s_addc_u32 s15, s15, 0
	s_cmp_gt_u32 s48, 29
	s_cbranch_scc0 .LBB0_101
	s_and_b64 vcc, exec, s[6:7]
	s_cbranch_vccz .LBB0_104
	s_barrier

.LBB0_122:
	s_add_u32 s20, s8, s18
	s_addc_u32 s21, s9, s19
	s_add_i32 s56, 0, 0x10000
	s_cmp_eq_u32 s55, 28
	s_cselect_b32 s23, s37, s21
	s_cselect_b32 s22, s51, s20
	s_cselect_b32 s21, s11, s54
	s_cselect_b32 s20, s52, s53
	s_add_i32 s58, 0, 0x14000
	v_add_u32_e32 v160, s56, v146
	v_add_u32_e32 v176, s58, v146
	ds_read_b128 v[148:151], v160
	ds_read_b128 v[152:155], v160 offset:1024
	ds_read_b128 v[156:159], v160 offset:2048
	ds_read_b128 v[160:163], v160 offset:3072
	ds_read_b128 v[164:167], v176
	ds_read_b128 v[168:171], v176 offset:1024
	ds_read_b128 v[172:175], v176 offset:2048
	ds_read_b128 v[176:179], v176 offset:3072
	v_lshl_add_u64 v[212:213], s[8:9], 0, v[140:141]
	s_add_i32 m0, s42, 0xc000
	ds_read_b128 v[180:183], v147
	ds_read_b128 v[184:187], v147 offset:1024
	ds_read_b128 v[188:191], v147 offset:2048
	ds_read_b128 v[192:195], v147 offset:3072
	ds_read_b128 v[196:199], v147 offset:4096
	ds_read_b128 v[200:203], v147 offset:5120
	ds_read_b128 v[204:207], v147 offset:6144
	ds_read_b128 v[208:211], v147 offset:7168
	global_load_lds_dwordx4 v[212:213], off
	v_lshl_add_u64 v[212:213], s[8:9], 0, v[142:143]
	s_add_i32 m0, s42, 0xe000
	s_nop 0
	global_load_lds_dwordx4 v[212:213], off
	s_waitcnt vmcnt(8)
	s_waitcnt lgkmcnt(0)
	s_barrier
	s_setprio 1
	s_waitcnt lgkmcnt(0)
	v_mfma_f32_16x16x32_bf16 v[92:95], v[148:151], v[180:183], v[92:95]
	v_mfma_f32_16x16x32_bf16 v[60:63], v[156:159], v[180:183], v[60:63]
	v_mfma_f32_16x16x32_bf16 v[88:91], v[148:151], v[188:191], v[88:91]
	v_mfma_f32_16x16x32_bf16 v[56:59], v[156:159], v[188:191], v[56:59]
	v_mfma_f32_16x16x32_bf16 v[84:87], v[148:151], v[196:199], v[84:87]
	v_mfma_f32_16x16x32_bf16 v[52:55], v[156:159], v[196:199], v[52:55]
	v_mfma_f32_16x16x32_bf16 v[80:83], v[148:151], v[204:207], v[80:83]
	v_mfma_f32_16x16x32_bf16 v[48:51], v[156:159], v[204:207], v[48:51]
	v_mfma_f32_16x16x32_bf16 v[92:95], v[152:155], v[184:187], v[92:95]
	v_mfma_f32_16x16x32_bf16 v[60:63], v[160:163], v[184:187], v[60:63]
	v_mfma_f32_16x16x32_bf16 v[88:91], v[152:155], v[192:195], v[88:91]
	v_mfma_f32_16x16x32_bf16 v[56:59], v[160:163], v[192:195], v[56:59]
	v_mfma_f32_16x16x32_bf16 v[84:87], v[152:155], v[200:203], v[84:87]
	v_mfma_f32_16x16x32_bf16 v[52:55], v[160:163], v[200:203], v[52:55]
	v_mfma_f32_16x16x32_bf16 v[80:83], v[152:155], v[208:211], v[80:83]
	v_mfma_f32_16x16x32_bf16 v[48:51], v[160:163], v[208:211], v[48:51]
	v_mfma_f32_16x16x32_bf16 v[28:31], v[164:167], v[180:183], v[28:31]
	v_mfma_f32_16x16x32_bf16 v[12:15], v[172:175], v[180:183], v[12:15]
	v_mfma_f32_16x16x32_bf16 v[24:27], v[164:167], v[188:191], v[24:27]
	v_mfma_f32_16x16x32_bf16 v[8:11], v[172:175], v[188:191], v[8:11]
	v_mfma_f32_16x16x32_bf16 v[20:23], v[164:167], v[196:199], v[20:23]
	v_mfma_f32_16x16x32_bf16 v[4:7], v[172:175], v[196:199], v[4:7]
	v_mfma_f32_16x16x32_bf16 v[16:19], v[164:167], v[204:207], v[16:19]
	v_mfma_f32_16x16x32_bf16 v[0:3], v[172:175], v[204:207], v[0:3]
	v_mfma_f32_16x16x32_bf16 v[28:31], v[168:171], v[184:187], v[28:31]
	v_mfma_f32_16x16x32_bf16 v[12:15], v[176:179], v[184:187], v[12:15]
	v_mfma_f32_16x16x32_bf16 v[24:27], v[168:171], v[192:195], v[24:27]
	v_mfma_f32_16x16x32_bf16 v[8:11], v[176:179], v[192:195], v[8:11]
	v_mfma_f32_16x16x32_bf16 v[20:23], v[168:171], v[200:203], v[20:23]
	v_mfma_f32_16x16x32_bf16 v[4:7], v[176:179], v[200:203], v[4:7]
	v_mfma_f32_16x16x32_bf16 v[16:19], v[168:171], v[208:211], v[16:19]
	v_mfma_f32_16x16x32_bf16 v[0:3], v[176:179], v[208:211], v[0:3]
	s_setprio 0
	s_barrier
	s_add_i32 s56, s56, s31
	v_lshl_add_u64 v[212:213], s[20:21], 0, v[128:129]
	s_mov_b32 m0, s56
	ds_read_b128 v[180:183], v147 offset:16384
	ds_read_b128 v[184:187], v147 offset:17408
	ds_read_b128 v[188:191], v147 offset:18432
	ds_read_b128 v[192:195], v147 offset:19456
	ds_read_b128 v[196:199], v147 offset:20480
	ds_read_b128 v[200:203], v147 offset:21504
	ds_read_b128 v[204:207], v147 offset:22528
	ds_read_b128 v[208:211], v147 offset:23552
	global_load_lds_dwordx4 v[212:213], off
	s_add_i32 m0, s56, 0x2000
	s_add_u32 s56, s20, 0x80000
	v_lshl_add_u64 v[212:213], s[20:21], 0, v[130:131]
	s_addc_u32 s57, s21, 0
	s_add_i32 s58, s58, s31
	global_load_lds_dwordx4 v[212:213], off
	v_lshl_add_u64 v[212:213], s[56:57], 0, v[128:129]
	s_mov_b32 m0, s58
	v_lshl_add_u64 v[214:215], s[22:23], 0, v[132:133]
	global_load_lds_dwordx4 v[212:213], off
	v_lshl_add_u64 v[212:213], s[56:57], 0, v[130:131]
	s_add_i32 m0, s58, 0x2000
	s_nop 0
	global_load_lds_dwordx4 v[212:213], off
	v_lshl_add_u64 v[212:213], s[22:23], 0, v[134:135]
	s_mov_b32 m0, s42
	s_nop 0
	global_load_lds_dwordx4 v[212:213], off
	s_mov_b32 m0, s43
	s_nop 0
	global_load_lds_dwordx4 v[214:215], off
	s_waitcnt vmcnt(8)
	s_waitcnt lgkmcnt(0)
	s_barrier
	s_setprio 1
	s_waitcnt lgkmcnt(0)
	v_mfma_f32_16x16x32_bf16 v[124:127], v[148:151], v[180:183], v[124:127]
	v_mfma_f32_16x16x32_bf16 v[108:111], v[156:159], v[180:183], v[108:111]
	v_mfma_f32_16x16x32_bf16 v[120:123], v[148:151], v[188:191], v[120:123]
	v_mfma_f32_16x16x32_bf16 v[104:107], v[156:159], v[188:191], v[104:107]
	v_mfma_f32_16x16x32_bf16 v[116:119], v[148:151], v[196:199], v[116:119]
	v_mfma_f32_16x16x32_bf16 v[100:103], v[156:159], v[196:199], v[100:103]
	v_mfma_f32_16x16x32_bf16 v[112:115], v[148:151], v[204:207], v[112:115]
	v_mfma_f32_16x16x32_bf16 v[96:99], v[156:159], v[204:207], v[96:99]
	v_mfma_f32_16x16x32_bf16 v[124:127], v[152:155], v[184:187], v[124:127]
	v_mfma_f32_16x16x32_bf16 v[108:111], v[160:163], v[184:187], v[108:111]
	v_mfma_f32_16x16x32_bf16 v[120:123], v[152:155], v[192:195], v[120:123]
	v_mfma_f32_16x16x32_bf16 v[104:107], v[160:163], v[192:195], v[104:107]
	v_mfma_f32_16x16x32_bf16 v[116:119], v[152:155], v[200:203], v[116:119]
	v_mfma_f32_16x16x32_bf16 v[100:103], v[160:163], v[200:203], v[100:103]
	v_mfma_f32_16x16x32_bf16 v[112:115], v[152:155], v[208:211], v[112:115]
	v_mfma_f32_16x16x32_bf16 v[96:99], v[160:163], v[208:211], v[96:99]
	v_mfma_f32_16x16x32_bf16 v[76:79], v[164:167], v[180:183], v[76:79]
	v_mfma_f32_16x16x32_bf16 v[44:47], v[172:175], v[180:183], v[44:47]
	v_mfma_f32_16x16x32_bf16 v[72:75], v[164:167], v[188:191], v[72:75]
	v_mfma_f32_16x16x32_bf16 v[40:43], v[172:175], v[188:191], v[40:43]
	v_mfma_f32_16x16x32_bf16 v[68:71], v[164:167], v[196:199], v[68:71]
	v_mfma_f32_16x16x32_bf16 v[36:39], v[172:175], v[196:199], v[36:39]
	v_mfma_f32_16x16x32_bf16 v[64:67], v[164:167], v[204:207], v[64:67]
	v_mfma_f32_16x16x32_bf16 v[32:35], v[172:175], v[204:207], v[32:35]
	v_mfma_f32_16x16x32_bf16 v[76:79], v[168:171], v[184:187], v[76:79]
	v_mfma_f32_16x16x32_bf16 v[44:47], v[176:179], v[184:187], v[44:47]
	v_mfma_f32_16x16x32_bf16 v[72:75], v[168:171], v[192:195], v[72:75]
	v_mfma_f32_16x16x32_bf16 v[40:43], v[176:179], v[192:195], v[40:43]
	v_mfma_f32_16x16x32_bf16 v[68:71], v[168:171], v[200:203], v[68:71]
	v_mfma_f32_16x16x32_bf16 v[36:39], v[176:179], v[200:203], v[36:39]
	v_mfma_f32_16x16x32_bf16 v[64:67], v[168:171], v[208:211], v[64:67]
	v_mfma_f32_16x16x32_bf16 v[32:35], v[176:179], v[208:211], v[32:35]
	s_setprio 0
	s_barrier
	s_add_i32 s56, 0, 0x18000
	s_add_i32 s57, 0, 0x1c000
	v_add_u32_e32 v160, s56, v146
	v_add_u32_e32 v176, s57, v146
	ds_read_b128 v[148:151], v160
	ds_read_b128 v[152:155], v160 offset:1024
	ds_read_b128 v[156:159], v160 offset:2048
	ds_read_b128 v[160:163], v160 offset:3072
	ds_read_b128 v[164:167], v176
	ds_read_b128 v[168:171], v176 offset:1024
	ds_read_b128 v[172:175], v176 offset:2048
	ds_read_b128 v[176:179], v176 offset:3072
	s_add_u32 s22, s22, 0x80000
	s_addc_u32 s23, s23, 0
	s_mov_b32 m0, s44
	v_lshl_add_u64 v[216:217], s[22:23], 0, v[134:135]
	ds_read_b128 v[180:183], v147 offset:32768
	ds_read_b128 v[184:187], v147 offset:33792
	ds_read_b128 v[188:191], v147 offset:34816
	ds_read_b128 v[192:195], v147 offset:35840
	ds_read_b128 v[196:199], v147 offset:36864
	ds_read_b128 v[200:203], v147 offset:37888
	ds_read_b128 v[204:207], v147 offset:38912
	ds_read_b128 v[208:211], v147 offset:39936
	global_load_lds_dwordx4 v[216:217], off
	v_lshl_add_u64 v[216:217], s[22:23], 0, v[132:133]
	s_mov_b32 m0, s45
	s_nop 0
	global_load_lds_dwordx4 v[216:217], off
	s_waitcnt vmcnt(8)
	s_waitcnt lgkmcnt(0)
	s_barrier
	s_setprio 1
	s_waitcnt lgkmcnt(0)
	v_mfma_f32_16x16x32_bf16 v[92:95], v[148:151], v[180:183], v[92:95]
	v_mfma_f32_16x16x32_bf16 v[60:63], v[156:159], v[180:183], v[60:63]
	v_mfma_f32_16x16x32_bf16 v[88:91], v[148:151], v[188:191], v[88:91]
	v_mfma_f32_16x16x32_bf16 v[56:59], v[156:159], v[188:191], v[56:59]
	v_mfma_f32_16x16x32_bf16 v[84:87], v[148:151], v[196:199], v[84:87]
	v_mfma_f32_16x16x32_bf16 v[52:55], v[156:159], v[196:199], v[52:55]
	v_mfma_f32_16x16x32_bf16 v[80:83], v[148:151], v[204:207], v[80:83]
	v_mfma_f32_16x16x32_bf16 v[48:51], v[156:159], v[204:207], v[48:51]
	v_mfma_f32_16x16x32_bf16 v[92:95], v[152:155], v[184:187], v[92:95]
	v_mfma_f32_16x16x32_bf16 v[60:63], v[160:163], v[184:187], v[60:63]
	v_mfma_f32_16x16x32_bf16 v[88:91], v[152:155], v[192:195], v[88:91]
	v_mfma_f32_16x16x32_bf16 v[56:59], v[160:163], v[192:195], v[56:59]
	v_mfma_f32_16x16x32_bf16 v[84:87], v[152:155], v[200:203], v[84:87]
	v_mfma_f32_16x16x32_bf16 v[52:55], v[160:163], v[200:203], v[52:55]
	v_mfma_f32_16x16x32_bf16 v[80:83], v[152:155], v[208:211], v[80:83]
	v_mfma_f32_16x16x32_bf16 v[48:51], v[160:163], v[208:211], v[48:51]
	v_mfma_f32_16x16x32_bf16 v[28:31], v[164:167], v[180:183], v[28:31]
	v_mfma_f32_16x16x32_bf16 v[12:15], v[172:175], v[180:183], v[12:15]
	v_mfma_f32_16x16x32_bf16 v[24:27], v[164:167], v[188:191], v[24:27]
	v_mfma_f32_16x16x32_bf16 v[8:11], v[172:175], v[188:191], v[8:11]
	v_mfma_f32_16x16x32_bf16 v[20:23], v[164:167], v[196:199], v[20:23]
	v_mfma_f32_16x16x32_bf16 v[4:7], v[172:175], v[196:199], v[4:7]
	v_mfma_f32_16x16x32_bf16 v[16:19], v[164:167], v[204:207], v[16:19]
	v_mfma_f32_16x16x32_bf16 v[0:3], v[172:175], v[204:207], v[0:3]
	v_mfma_f32_16x16x32_bf16 v[28:31], v[168:171], v[184:187], v[28:31]
	v_mfma_f32_16x16x32_bf16 v[12:15], v[176:179], v[184:187], v[12:15]
	v_mfma_f32_16x16x32_bf16 v[24:27], v[168:171], v[192:195], v[24:27]
	v_mfma_f32_16x16x32_bf16 v[8:11], v[176:179], v[192:195], v[8:11]
	v_mfma_f32_16x16x32_bf16 v[20:23], v[168:171], v[200:203], v[20:23]
	v_mfma_f32_16x16x32_bf16 v[4:7], v[176:179], v[200:203], v[4:7]
	v_mfma_f32_16x16x32_bf16 v[16:19], v[168:171], v[208:211], v[16:19]
	v_mfma_f32_16x16x32_bf16 v[0:3], v[176:179], v[208:211], v[0:3]
	s_setprio 0
	s_barrier
	s_add_u32 s22, s20, 0x4000
	s_addc_u32 s23, s21, 0
	s_add_i32 s56, s56, s31
	v_lshl_add_u64 v[216:217], s[22:23], 0, v[128:129]
	s_mov_b32 m0, s56
	ds_read_b128 v[180:183], v147 offset:49152
	ds_read_b128 v[184:187], v147 offset:50176
	ds_read_b128 v[188:191], v147 offset:51200
	ds_read_b128 v[192:195], v147 offset:52224
	ds_read_b128 v[196:199], v147 offset:53248
	ds_read_b128 v[200:203], v147 offset:54272
	ds_read_b128 v[204:207], v147 offset:55296
	ds_read_b128 v[208:211], v147 offset:56320
	global_load_lds_dwordx4 v[216:217], off
	s_add_i32 m0, s56, 0x2000
	s_add_u32 s20, s20, 0x84000
	v_lshl_add_u64 v[216:217], s[22:23], 0, v[130:131]
	s_addc_u32 s21, s21, 0
	s_add_i32 s22, s57, s31
	global_load_lds_dwordx4 v[216:217], off
	v_lshl_add_u64 v[216:217], s[20:21], 0, v[128:129]
	s_mov_b32 m0, s22
	v_lshl_add_u64 v[212:213], v[212:213], 0, s[34:35]
	global_load_lds_dwordx4 v[216:217], off
	v_lshl_add_u64 v[216:217], s[20:21], 0, v[130:131]
	s_add_i32 m0, s22, 0x2000
	s_nop 0
	global_load_lds_dwordx4 v[216:217], off
	s_mov_b32 m0, s47
	s_nop 0
	global_load_lds_dwordx4 v[212:213], off
	v_lshl_add_u64 v[212:213], v[214:215], 0, s[34:35]
	s_mov_b32 m0, s48
	s_nop 0
	global_load_lds_dwordx4 v[212:213], off
	s_waitcnt vmcnt(8)
	s_waitcnt lgkmcnt(0)
	s_barrier
	s_setprio 1
	s_waitcnt lgkmcnt(0)
	v_mfma_f32_16x16x32_bf16 v[124:127], v[148:151], v[180:183], v[124:127]
	v_mfma_f32_16x16x32_bf16 v[108:111], v[156:159], v[180:183], v[108:111]
	v_mfma_f32_16x16x32_bf16 v[120:123], v[148:151], v[188:191], v[120:123]
	v_mfma_f32_16x16x32_bf16 v[104:107], v[156:159], v[188:191], v[104:107]
	v_mfma_f32_16x16x32_bf16 v[116:119], v[148:151], v[196:199], v[116:119]
	v_mfma_f32_16x16x32_bf16 v[100:103], v[156:159], v[196:199], v[100:103]
	v_mfma_f32_16x16x32_bf16 v[112:115], v[148:151], v[204:207], v[112:115]
	v_mfma_f32_16x16x32_bf16 v[96:99], v[156:159], v[204:207], v[96:99]
	v_mfma_f32_16x16x32_bf16 v[124:127], v[152:155], v[184:187], v[124:127]
	v_mfma_f32_16x16x32_bf16 v[108:111], v[160:163], v[184:187], v[108:111]
	v_mfma_f32_16x16x32_bf16 v[120:123], v[152:155], v[192:195], v[120:123]
	v_mfma_f32_16x16x32_bf16 v[104:107], v[160:163], v[192:195], v[104:107]
	v_mfma_f32_16x16x32_bf16 v[116:119], v[152:155], v[200:203], v[116:119]
	v_mfma_f32_16x16x32_bf16 v[100:103], v[160:163], v[200:203], v[100:103]
	v_mfma_f32_16x16x32_bf16 v[112:115], v[152:155], v[208:211], v[112:115]
	v_mfma_f32_16x16x32_bf16 v[96:99], v[160:163], v[208:211], v[96:99]
	v_mfma_f32_16x16x32_bf16 v[76:79], v[164:167], v[180:183], v[76:79]
	v_mfma_f32_16x16x32_bf16 v[44:47], v[172:175], v[180:183], v[44:47]
	v_mfma_f32_16x16x32_bf16 v[72:75], v[164:167], v[188:191], v[72:75]
	v_mfma_f32_16x16x32_bf16 v[40:43], v[172:175], v[188:191], v[40:43]
	v_mfma_f32_16x16x32_bf16 v[68:71], v[164:167], v[196:199], v[68:71]
	v_mfma_f32_16x16x32_bf16 v[36:39], v[172:175], v[196:199], v[36:39]
	v_mfma_f32_16x16x32_bf16 v[64:67], v[164:167], v[204:207], v[64:67]
	v_mfma_f32_16x16x32_bf16 v[32:35], v[172:175], v[204:207], v[32:35]
	v_mfma_f32_16x16x32_bf16 v[76:79], v[168:171], v[184:187], v[76:79]
	v_mfma_f32_16x16x32_bf16 v[44:47], v[176:179], v[184:187], v[44:47]
	v_mfma_f32_16x16x32_bf16 v[72:75], v[168:171], v[192:195], v[72:75]
	v_mfma_f32_16x16x32_bf16 v[40:43], v[176:179], v[192:195], v[40:43]
	v_mfma_f32_16x16x32_bf16 v[68:71], v[168:171], v[200:203], v[68:71]
	v_mfma_f32_16x16x32_bf16 v[36:39], v[176:179], v[200:203], v[36:39]
	v_mfma_f32_16x16x32_bf16 v[64:67], v[168:171], v[208:211], v[64:67]
	v_mfma_f32_16x16x32_bf16 v[32:35], v[176:179], v[208:211], v[32:35]
	s_setprio 0
	s_barrier
	s_add_i32 s55, s55, 2
	s_add_u32 s53, s53, 0x8000
	s_addc_u32 s54, s54, 0
	s_add_u32 s18, s18, 0x100
	s_addc_u32 s19, s19, 0
	v_lshl_add_u64 v[142:143], v[142:143], 0, s[12:13]
	s_cmp_gt_u32 s55, 29
	v_lshl_add_u64 v[140:141], v[140:141], 0, s[12:13]
	s_cbranch_scc0 .LBB0_122
	s_andn2_b64 vcc, exec, s[40:41]
	s_cbranch_vccnz .LBB0_114
	v_mov_b32_e32 v32, 0
	s_mov_b32 s6, s10
	s_mov_b32 s27, s36
	s_mov_b64 s[4:5], s[16:17]
	s_mov_b64 s[8:9], s[14:15]
	s_mov_b32 s49, s50
	v_mov_b32_e32 v33, v32
	v_mov_b32_e32 v34, v32
	v_mov_b32_e32 v35, v32
	v_mov_b32_e32 v64, v32
	v_mov_b32_e32 v65, v32
	v_mov_b32_e32 v66, v32
	v_mov_b32_e32 v67, v32
	v_mov_b32_e32 v36, v32
	v_mov_b32_e32 v37, v32
	v_mov_b32_e32 v38, v32
	v_mov_b32_e32 v39, v32
	v_mov_b32_e32 v68, v32
	v_mov_b32_e32 v69, v32
	v_mov_b32_e32 v70, v32
	v_mov_b32_e32 v71, v32
	v_mov_b32_e32 v40, v32
	v_mov_b32_e32 v41, v32
	v_mov_b32_e32 v42, v32
	v_mov_b32_e32 v43, v32
	v_mov_b32_e32 v72, v32
	v_mov_b32_e32 v73, v32
	v_mov_b32_e32 v74, v32
	v_mov_b32_e32 v75, v32
	v_mov_b32_e32 v44, v32
	v_mov_b32_e32 v45, v32
	v_mov_b32_e32 v46, v32
	v_mov_b32_e32 v47, v32
	v_mov_b32_e32 v76, v32
	v_mov_b32_e32 v77, v32
	v_mov_b32_e32 v78, v32
	v_mov_b32_e32 v79, v32
	v_mov_b32_e32 v96, v32
	v_mov_b32_e32 v97, v32
	v_mov_b32_e32 v98, v32
	v_mov_b32_e32 v99, v32
	v_mov_b32_e32 v112, v32
	v_mov_b32_e32 v113, v32
	v_mov_b32_e32 v114, v32
	v_mov_b32_e32 v115, v32
	v_mov_b32_e32 v100, v32
	v_mov_b32_e32 v101, v32
	v_mov_b32_e32 v102, v32
	v_mov_b32_e32 v103, v32
	v_mov_b32_e32 v116, v32
	v_mov_b32_e32 v117, v32
	v_mov_b32_e32 v118, v32
	v_mov_b32_e32 v119, v32
	v_mov_b32_e32 v104, v32
	v_mov_b32_e32 v105, v32
	v_mov_b32_e32 v106, v32
	v_mov_b32_e32 v107, v32
	v_mov_b32_e32 v120, v32
	v_mov_b32_e32 v121, v32
	v_mov_b32_e32 v122, v32
	v_mov_b32_e32 v123, v32
	v_mov_b32_e32 v108, v32
	v_mov_b32_e32 v109, v32
	v_mov_b32_e32 v110, v32
	v_mov_b32_e32 v111, v32
	v_mov_b32_e32 v124, v32
	v_mov_b32_e32 v125, v32
	v_mov_b32_e32 v126, v32
	v_mov_b32_e32 v127, v32
	v_mov_b32_e32 v0, v32
	v_mov_b32_e32 v1, v32
	v_mov_b32_e32 v2, v32
	v_mov_b32_e32 v3, v32
	v_mov_b32_e32 v16, v32
	v_mov_b32_e32 v17, v32
	v_mov_b32_e32 v18, v32
	v_mov_b32_e32 v19, v32
	v_mov_b32_e32 v4, v32
	v_mov_b32_e32 v5, v32
	v_mov_b32_e32 v6, v32
	v_mov_b32_e32 v7, v32
	v_mov_b32_e32 v20, v32
	v_mov_b32_e32 v21, v32
	v_mov_b32_e32 v22, v32
	v_mov_b32_e32 v23, v32
	v_mov_b32_e32 v8, v32
	v_mov_b32_e32 v9, v32
	v_mov_b32_e32 v10, v32
	v_mov_b32_e32 v11, v32
	v_mov_b32_e32 v24, v32
	v_mov_b32_e32 v25, v32
	v_mov_b32_e32 v26, v32
	v_mov_b32_e32 v27, v32
	v_mov_b32_e32 v12, v32
	v_mov_b32_e32 v13, v32
	v_mov_b32_e32 v14, v32
	v_mov_b32_e32 v15, v32
	v_mov_b32_e32 v28, v32
	v_mov_b32_e32 v29, v32
	v_mov_b32_e32 v30, v32
	v_mov_b32_e32 v31, v32
	v_mov_b32_e32 v48, v32
	v_mov_b32_e32 v49, v32
	v_mov_b32_e32 v50, v32
	v_mov_b32_e32 v51, v32
	v_mov_b32_e32 v80, v32
	v_mov_b32_e32 v81, v32
	v_mov_b32_e32 v82, v32
	v_mov_b32_e32 v83, v32
	v_mov_b32_e32 v52, v32
	v_mov_b32_e32 v53, v32
	v_mov_b32_e32 v54, v32
	v_mov_b32_e32 v55, v32
	v_mov_b32_e32 v84, v32
	v_mov_b32_e32 v85, v32
	v_mov_b32_e32 v86, v32
	v_mov_b32_e32 v87, v32
	v_mov_b32_e32 v56, v32
	v_mov_b32_e32 v57, v32
	v_mov_b32_e32 v58, v32
	v_mov_b32_e32 v59, v32
	v_mov_b32_e32 v88, v32
	v_mov_b32_e32 v89, v32
	v_mov_b32_e32 v90, v32
	v_mov_b32_e32 v91, v32
	v_mov_b32_e32 v60, v32
	v_mov_b32_e32 v61, v32
	v_mov_b32_e32 v62, v32
	v_mov_b32_e32 v63, v32
	v_mov_b32_e32 v92, v32
	v_mov_b32_e32 v93, v32
	v_mov_b32_e32 v94, v32
	v_mov_b32_e32 v95, v32
	s_branch .LBB0_114

.LBB0_550:
	s_add_u32 s16, s14, 0xfff80080
	s_addc_u32 s17, s15, -1
	s_add_i32 s49, 0, 0x10000
	s_cmp_eq_u32 s48, 28
	s_cselect_b32 s19, s11, s17
	s_cselect_b32 s18, s44, s16
	s_cselect_b32 s17, s9, s47
	s_cselect_b32 s16, s45, s46
	s_add_i32 s52, 0, 0x14000
	v_add_u32_e32 v156, s49, v145
	v_add_u32_e32 v172, s52, v145
	ds_read_b128 v[140:143], v156
	ds_read_b128 v[148:151], v156 offset:1024
	ds_read_b128 v[152:155], v156 offset:2048
	ds_read_b128 v[156:159], v156 offset:3072
	ds_read_b128 v[160:163], v172
	ds_read_b128 v[164:167], v172 offset:1024
	ds_read_b128 v[168:171], v172 offset:2048
	ds_read_b128 v[172:175], v172 offset:3072
	v_lshl_add_u64 v[208:209], s[14:15], 0, v[138:139]
	s_add_i32 m0, s24, 0xc000
	ds_read_b128 v[176:179], v147
	ds_read_b128 v[180:183], v147 offset:1024
	ds_read_b128 v[184:187], v147 offset:2048
	ds_read_b128 v[188:191], v147 offset:3072
	ds_read_b128 v[192:195], v147 offset:4096
	ds_read_b128 v[196:199], v147 offset:5120
	ds_read_b128 v[200:203], v147 offset:6144
	ds_read_b128 v[204:207], v147 offset:7168
	global_load_lds_dwordx4 v[208:209], off
	v_lshl_add_u64 v[208:209], s[14:15], 0, v[136:137]
	s_add_i32 m0, s24, 0xe000
	s_nop 0
	global_load_lds_dwordx4 v[208:209], off
	s_waitcnt vmcnt(8)
	s_waitcnt lgkmcnt(0)
	s_barrier
	s_setprio 1
	s_waitcnt lgkmcnt(0)
	v_mfma_f32_16x16x32_bf16 v[124:127], v[140:143], v[176:179], v[124:127]
	v_mfma_f32_16x16x32_bf16 v[120:123], v[152:155], v[176:179], v[120:123]
	v_mfma_f32_16x16x32_bf16 v[116:119], v[140:143], v[184:187], v[116:119]
	v_mfma_f32_16x16x32_bf16 v[108:111], v[152:155], v[184:187], v[108:111]
	v_mfma_f32_16x16x32_bf16 v[100:103], v[140:143], v[192:195], v[100:103]
	v_mfma_f32_16x16x32_bf16 v[92:95], v[152:155], v[192:195], v[92:95]
	v_mfma_f32_16x16x32_bf16 v[84:87], v[140:143], v[200:203], v[84:87]
	v_mfma_f32_16x16x32_bf16 v[76:79], v[152:155], v[200:203], v[76:79]
	v_mfma_f32_16x16x32_bf16 v[124:127], v[148:151], v[180:183], v[124:127]
	v_mfma_f32_16x16x32_bf16 v[120:123], v[156:159], v[180:183], v[120:123]
	v_mfma_f32_16x16x32_bf16 v[116:119], v[148:151], v[188:191], v[116:119]
	v_mfma_f32_16x16x32_bf16 v[108:111], v[156:159], v[188:191], v[108:111]
	v_mfma_f32_16x16x32_bf16 v[100:103], v[148:151], v[196:199], v[100:103]
	v_mfma_f32_16x16x32_bf16 v[92:95], v[156:159], v[196:199], v[92:95]
	v_mfma_f32_16x16x32_bf16 v[84:87], v[148:151], v[204:207], v[84:87]
	v_mfma_f32_16x16x32_bf16 v[76:79], v[156:159], v[204:207], v[76:79]
	v_mfma_f32_16x16x32_bf16 v[112:115], v[160:163], v[176:179], v[112:115]
	v_mfma_f32_16x16x32_bf16 v[104:107], v[168:171], v[176:179], v[104:107]
	v_mfma_f32_16x16x32_bf16 v[96:99], v[160:163], v[184:187], v[96:99]
	v_mfma_f32_16x16x32_bf16 v[88:91], v[168:171], v[184:187], v[88:91]
	v_mfma_f32_16x16x32_bf16 v[80:83], v[160:163], v[192:195], v[80:83]
	v_mfma_f32_16x16x32_bf16 v[72:75], v[168:171], v[192:195], v[72:75]
	v_mfma_f32_16x16x32_bf16 v[68:71], v[160:163], v[200:203], v[68:71]
	v_mfma_f32_16x16x32_bf16 v[64:67], v[168:171], v[200:203], v[64:67]
	v_mfma_f32_16x16x32_bf16 v[112:115], v[164:167], v[180:183], v[112:115]
	v_mfma_f32_16x16x32_bf16 v[104:107], v[172:175], v[180:183], v[104:107]
	v_mfma_f32_16x16x32_bf16 v[96:99], v[164:167], v[188:191], v[96:99]
	v_mfma_f32_16x16x32_bf16 v[88:91], v[172:175], v[188:191], v[88:91]
	v_mfma_f32_16x16x32_bf16 v[80:83], v[164:167], v[196:199], v[80:83]
	v_mfma_f32_16x16x32_bf16 v[72:75], v[172:175], v[196:199], v[72:75]
	v_mfma_f32_16x16x32_bf16 v[68:71], v[164:167], v[204:207], v[68:71]
	v_mfma_f32_16x16x32_bf16 v[64:67], v[172:175], v[204:207], v[64:67]
	s_setprio 0
	s_barrier
	s_add_i32 s49, s49, s23
	v_lshl_add_u64 v[208:209], s[16:17], 0, v[134:135]
	s_mov_b32 m0, s49
	ds_read_b128 v[176:179], v147 offset:16384
	ds_read_b128 v[180:183], v147 offset:17408
	ds_read_b128 v[184:187], v147 offset:18432
	ds_read_b128 v[188:191], v147 offset:19456
	ds_read_b128 v[192:195], v147 offset:20480
	ds_read_b128 v[196:199], v147 offset:21504
	ds_read_b128 v[200:203], v147 offset:22528
	ds_read_b128 v[204:207], v147 offset:23552
	global_load_lds_dwordx4 v[208:209], off
	s_add_i32 m0, s49, 0x2000
	s_add_u32 s50, s16, 0x80000
	v_lshl_add_u64 v[208:209], s[16:17], 0, v[130:131]
	s_addc_u32 s51, s17, 0
	s_add_i32 s49, s52, s23
	global_load_lds_dwordx4 v[208:209], off
	v_lshl_add_u64 v[208:209], s[50:51], 0, v[134:135]
	s_mov_b32 m0, s49
	v_lshl_add_u64 v[210:211], s[18:19], 0, v[132:133]
	global_load_lds_dwordx4 v[208:209], off
	v_lshl_add_u64 v[208:209], s[50:51], 0, v[130:131]
	s_add_i32 m0, s49, 0x2000
	s_nop 0
	global_load_lds_dwordx4 v[208:209], off
	v_lshl_add_u64 v[208:209], s[18:19], 0, v[128:129]
	s_mov_b32 m0, s24
	s_nop 0
	global_load_lds_dwordx4 v[208:209], off
	s_mov_b32 m0, s25
	s_nop 0
	global_load_lds_dwordx4 v[210:211], off
	s_waitcnt vmcnt(8)
	s_waitcnt lgkmcnt(0)
	s_barrier
	s_setprio 1
	s_waitcnt lgkmcnt(0)
	v_mfma_f32_16x16x32_bf16 v[60:63], v[140:143], v[176:179], v[60:63]
	v_mfma_f32_16x16x32_bf16 v[56:59], v[152:155], v[176:179], v[56:59]
	v_mfma_f32_16x16x32_bf16 v[52:55], v[140:143], v[184:187], v[52:55]
	v_mfma_f32_16x16x32_bf16 v[44:47], v[152:155], v[184:187], v[44:47]
	v_mfma_f32_16x16x32_bf16 v[36:39], v[140:143], v[192:195], v[36:39]
	v_mfma_f32_16x16x32_bf16 v[28:31], v[152:155], v[192:195], v[28:31]
	v_mfma_f32_16x16x32_bf16 v[20:23], v[140:143], v[200:203], v[20:23]
	v_mfma_f32_16x16x32_bf16 v[12:15], v[152:155], v[200:203], v[12:15]
	v_mfma_f32_16x16x32_bf16 v[60:63], v[148:151], v[180:183], v[60:63]
	v_mfma_f32_16x16x32_bf16 v[56:59], v[156:159], v[180:183], v[56:59]
	v_mfma_f32_16x16x32_bf16 v[52:55], v[148:151], v[188:191], v[52:55]
	v_mfma_f32_16x16x32_bf16 v[44:47], v[156:159], v[188:191], v[44:47]
	v_mfma_f32_16x16x32_bf16 v[36:39], v[148:151], v[196:199], v[36:39]
	v_mfma_f32_16x16x32_bf16 v[28:31], v[156:159], v[196:199], v[28:31]
	v_mfma_f32_16x16x32_bf16 v[20:23], v[148:151], v[204:207], v[20:23]
	v_mfma_f32_16x16x32_bf16 v[12:15], v[156:159], v[204:207], v[12:15]
	v_mfma_f32_16x16x32_bf16 v[48:51], v[160:163], v[176:179], v[48:51]
	v_mfma_f32_16x16x32_bf16 v[40:43], v[168:171], v[176:179], v[40:43]
	v_mfma_f32_16x16x32_bf16 v[32:35], v[160:163], v[184:187], v[32:35]
	v_mfma_f32_16x16x32_bf16 v[24:27], v[168:171], v[184:187], v[24:27]
	v_mfma_f32_16x16x32_bf16 v[16:19], v[160:163], v[192:195], v[16:19]
	v_mfma_f32_16x16x32_bf16 v[8:11], v[168:171], v[192:195], v[8:11]
	v_mfma_f32_16x16x32_bf16 v[4:7], v[160:163], v[200:203], v[4:7]
	v_mfma_f32_16x16x32_bf16 v[0:3], v[168:171], v[200:203], v[0:3]
	v_mfma_f32_16x16x32_bf16 v[48:51], v[164:167], v[180:183], v[48:51]
	v_mfma_f32_16x16x32_bf16 v[40:43], v[172:175], v[180:183], v[40:43]
	v_mfma_f32_16x16x32_bf16 v[32:35], v[164:167], v[188:191], v[32:35]
	v_mfma_f32_16x16x32_bf16 v[24:27], v[172:175], v[188:191], v[24:27]
	v_mfma_f32_16x16x32_bf16 v[16:19], v[164:167], v[196:199], v[16:19]
	v_mfma_f32_16x16x32_bf16 v[8:11], v[172:175], v[196:199], v[8:11]
	v_mfma_f32_16x16x32_bf16 v[4:7], v[164:167], v[204:207], v[4:7]
	v_mfma_f32_16x16x32_bf16 v[0:3], v[172:175], v[204:207], v[0:3]
	s_setprio 0
	s_barrier
	s_add_i32 s49, 0, 0x18000
	s_add_i32 s50, 0, 0x1c000
	v_add_u32_e32 v156, s49, v145
	v_add_u32_e32 v172, s50, v145
	ds_read_b128 v[140:143], v156
	ds_read_b128 v[148:151], v156 offset:1024
	ds_read_b128 v[152:155], v156 offset:2048
	ds_read_b128 v[156:159], v156 offset:3072
	ds_read_b128 v[160:163], v172
	ds_read_b128 v[164:167], v172 offset:1024
	ds_read_b128 v[168:171], v172 offset:2048
	ds_read_b128 v[172:175], v172 offset:3072
	s_add_u32 s18, s18, 0x80000
	s_addc_u32 s19, s19, 0
	s_mov_b32 m0, s26
	v_lshl_add_u64 v[212:213], s[18:19], 0, v[128:129]
	ds_read_b128 v[176:179], v147 offset:32768
	ds_read_b128 v[180:183], v147 offset:33792
	ds_read_b128 v[184:187], v147 offset:34816
	ds_read_b128 v[188:191], v147 offset:35840
	ds_read_b128 v[192:195], v147 offset:36864
	ds_read_b128 v[196:199], v147 offset:37888
	ds_read_b128 v[200:203], v147 offset:38912
	ds_read_b128 v[204:207], v147 offset:39936
	global_load_lds_dwordx4 v[212:213], off
	v_lshl_add_u64 v[212:213], s[18:19], 0, v[132:133]
	s_mov_b32 m0, s27
	s_nop 0
	global_load_lds_dwordx4 v[212:213], off
	s_waitcnt vmcnt(8)
	s_waitcnt lgkmcnt(0)
	s_barrier
	s_setprio 1
	s_waitcnt lgkmcnt(0)
	v_mfma_f32_16x16x32_bf16 v[124:127], v[140:143], v[176:179], v[124:127]
	v_mfma_f32_16x16x32_bf16 v[120:123], v[152:155], v[176:179], v[120:123]
	v_mfma_f32_16x16x32_bf16 v[116:119], v[140:143], v[184:187], v[116:119]
	v_mfma_f32_16x16x32_bf16 v[108:111], v[152:155], v[184:187], v[108:111]
	v_mfma_f32_16x16x32_bf16 v[100:103], v[140:143], v[192:195], v[100:103]
	v_mfma_f32_16x16x32_bf16 v[92:95], v[152:155], v[192:195], v[92:95]
	v_mfma_f32_16x16x32_bf16 v[84:87], v[140:143], v[200:203], v[84:87]
	v_mfma_f32_16x16x32_bf16 v[76:79], v[152:155], v[200:203], v[76:79]
	v_mfma_f32_16x16x32_bf16 v[124:127], v[148:151], v[180:183], v[124:127]
	v_mfma_f32_16x16x32_bf16 v[120:123], v[156:159], v[180:183], v[120:123]
	v_mfma_f32_16x16x32_bf16 v[116:119], v[148:151], v[188:191], v[116:119]
	v_mfma_f32_16x16x32_bf16 v[108:111], v[156:159], v[188:191], v[108:111]
	v_mfma_f32_16x16x32_bf16 v[100:103], v[148:151], v[196:199], v[100:103]
	v_mfma_f32_16x16x32_bf16 v[92:95], v[156:159], v[196:199], v[92:95]
	v_mfma_f32_16x16x32_bf16 v[84:87], v[148:151], v[204:207], v[84:87]
	v_mfma_f32_16x16x32_bf16 v[76:79], v[156:159], v[204:207], v[76:79]
	v_mfma_f32_16x16x32_bf16 v[112:115], v[160:163], v[176:179], v[112:115]
	v_mfma_f32_16x16x32_bf16 v[104:107], v[168:171], v[176:179], v[104:107]
	v_mfma_f32_16x16x32_bf16 v[96:99], v[160:163], v[184:187], v[96:99]
	v_mfma_f32_16x16x32_bf16 v[88:91], v[168:171], v[184:187], v[88:91]
	v_mfma_f32_16x16x32_bf16 v[80:83], v[160:163], v[192:195], v[80:83]
	v_mfma_f32_16x16x32_bf16 v[72:75], v[168:171], v[192:195], v[72:75]
	v_mfma_f32_16x16x32_bf16 v[68:71], v[160:163], v[200:203], v[68:71]
	v_mfma_f32_16x16x32_bf16 v[64:67], v[168:171], v[200:203], v[64:67]
	v_mfma_f32_16x16x32_bf16 v[112:115], v[164:167], v[180:183], v[112:115]
	v_mfma_f32_16x16x32_bf16 v[104:107], v[172:175], v[180:183], v[104:107]
	v_mfma_f32_16x16x32_bf16 v[96:99], v[164:167], v[188:191], v[96:99]
	v_mfma_f32_16x16x32_bf16 v[88:91], v[172:175], v[188:191], v[88:91]
	v_mfma_f32_16x16x32_bf16 v[80:83], v[164:167], v[196:199], v[80:83]
	v_mfma_f32_16x16x32_bf16 v[72:75], v[172:175], v[196:199], v[72:75]
	v_mfma_f32_16x16x32_bf16 v[68:71], v[164:167], v[204:207], v[68:71]
	v_mfma_f32_16x16x32_bf16 v[64:67], v[172:175], v[204:207], v[64:67]
	s_setprio 0
	s_barrier
	s_add_u32 s18, s16, 0x4000
	s_addc_u32 s19, s17, 0
	s_add_i32 s49, s49, s23
	v_lshl_add_u64 v[212:213], s[18:19], 0, v[134:135]
	s_mov_b32 m0, s49
	ds_read_b128 v[176:179], v147 offset:49152
	ds_read_b128 v[180:183], v147 offset:50176
	ds_read_b128 v[184:187], v147 offset:51200
	ds_read_b128 v[188:191], v147 offset:52224
	ds_read_b128 v[192:195], v147 offset:53248
	ds_read_b128 v[196:199], v147 offset:54272
	ds_read_b128 v[200:203], v147 offset:55296
	ds_read_b128 v[204:207], v147 offset:56320
	global_load_lds_dwordx4 v[212:213], off
	s_add_i32 m0, s49, 0x2000
	s_add_u32 s16, s16, 0x84000
	v_lshl_add_u64 v[212:213], s[18:19], 0, v[130:131]
	s_addc_u32 s17, s17, 0
	s_add_i32 s18, s50, s23
	global_load_lds_dwordx4 v[212:213], off
	v_lshl_add_u64 v[212:213], s[16:17], 0, v[134:135]
	s_mov_b32 m0, s18
	v_lshl_add_u64 v[208:209], v[208:209], 0, s[34:35]
	global_load_lds_dwordx4 v[212:213], off
	v_lshl_add_u64 v[212:213], s[16:17], 0, v[130:131]
	s_add_i32 m0, s18, 0x2000
	s_nop 0
	global_load_lds_dwordx4 v[212:213], off
	s_mov_b32 m0, s28
	s_nop 0
	global_load_lds_dwordx4 v[208:209], off
	v_lshl_add_u64 v[208:209], v[210:211], 0, s[34:35]
	s_mov_b32 m0, s29
	s_nop 0
	global_load_lds_dwordx4 v[208:209], off
	s_waitcnt vmcnt(8)
	s_waitcnt lgkmcnt(0)
	s_barrier
	s_setprio 1
	s_waitcnt lgkmcnt(0)
	v_mfma_f32_16x16x32_bf16 v[60:63], v[140:143], v[176:179], v[60:63]
	v_mfma_f32_16x16x32_bf16 v[56:59], v[152:155], v[176:179], v[56:59]
	v_mfma_f32_16x16x32_bf16 v[52:55], v[140:143], v[184:187], v[52:55]
	v_mfma_f32_16x16x32_bf16 v[44:47], v[152:155], v[184:187], v[44:47]
	v_mfma_f32_16x16x32_bf16 v[36:39], v[140:143], v[192:195], v[36:39]
	v_mfma_f32_16x16x32_bf16 v[28:31], v[152:155], v[192:195], v[28:31]
	v_mfma_f32_16x16x32_bf16 v[20:23], v[140:143], v[200:203], v[20:23]
	v_mfma_f32_16x16x32_bf16 v[12:15], v[152:155], v[200:203], v[12:15]
	v_mfma_f32_16x16x32_bf16 v[60:63], v[148:151], v[180:183], v[60:63]
	v_mfma_f32_16x16x32_bf16 v[56:59], v[156:159], v[180:183], v[56:59]
	v_mfma_f32_16x16x32_bf16 v[52:55], v[148:151], v[188:191], v[52:55]
	v_mfma_f32_16x16x32_bf16 v[44:47], v[156:159], v[188:191], v[44:47]
	v_mfma_f32_16x16x32_bf16 v[36:39], v[148:151], v[196:199], v[36:39]
	v_mfma_f32_16x16x32_bf16 v[28:31], v[156:159], v[196:199], v[28:31]
	v_mfma_f32_16x16x32_bf16 v[20:23], v[148:151], v[204:207], v[20:23]
	v_mfma_f32_16x16x32_bf16 v[12:15], v[156:159], v[204:207], v[12:15]
	v_mfma_f32_16x16x32_bf16 v[48:51], v[160:163], v[176:179], v[48:51]
	v_mfma_f32_16x16x32_bf16 v[40:43], v[168:171], v[176:179], v[40:43]
	v_mfma_f32_16x16x32_bf16 v[32:35], v[160:163], v[184:187], v[32:35]
	v_mfma_f32_16x16x32_bf16 v[24:27], v[168:171], v[184:187], v[24:27]
	v_mfma_f32_16x16x32_bf16 v[16:19], v[160:163], v[192:195], v[16:19]
	v_mfma_f32_16x16x32_bf16 v[8:11], v[168:171], v[192:195], v[8:11]
	v_mfma_f32_16x16x32_bf16 v[4:7], v[160:163], v[200:203], v[4:7]
	v_mfma_f32_16x16x32_bf16 v[0:3], v[168:171], v[200:203], v[0:3]
	v_mfma_f32_16x16x32_bf16 v[48:51], v[164:167], v[180:183], v[48:51]
	v_mfma_f32_16x16x32_bf16 v[40:43], v[172:175], v[180:183], v[40:43]
	v_mfma_f32_16x16x32_bf16 v[32:35], v[164:167], v[188:191], v[32:35]
	v_mfma_f32_16x16x32_bf16 v[24:27], v[172:175], v[188:191], v[24:27]
	v_mfma_f32_16x16x32_bf16 v[16:19], v[164:167], v[196:199], v[16:19]
	v_mfma_f32_16x16x32_bf16 v[8:11], v[172:175], v[196:199], v[8:11]
	v_mfma_f32_16x16x32_bf16 v[4:7], v[164:167], v[204:207], v[4:7]
	v_mfma_f32_16x16x32_bf16 v[0:3], v[172:175], v[204:207], v[0:3]
	s_setprio 0
	s_barrier
	s_add_i32 s48, s48, 2
	s_add_u32 s46, s46, 0x8000
	s_addc_u32 s47, s47, 0
	s_add_u32 s14, s14, 0x100
	s_addc_u32 s15, s15, 0
	s_cmp_gt_u32 s48, 29
	s_cbranch_scc0 .LBB0_550
	s_and_b64 vcc, exec, s[6:7]
	s_cbranch_vccz .LBB0_553
	s_barrier
